# residual tile L2 prefetch in the D1, D2 and OUT K-loops (two halves, six and four K-iterations before the end)
# baseline (speedup 1.0000x reference)
;     __host__ __device__ bool next(int i, Unit& u) const {
;         const long L = (long)i * G + c; if (L >= nwg) return false;
;         int wgid = (int)L; { const int q = nwg / NXCD, r = nwg % NXCD, xcd = wgid % NXCD, off = wgid / NXCD; wgid = (xcd < r ? xcd * (q + 1) : r * (q + 1) + (xcd - r) * q) + off; }
;         const int nig = WGM * nN, gid = wgid / nig, fm = gid * WGM, gsz = (nM - fm) < WGM ? (nM - fm) : WGM;
;         u.pm = fm + ((wgid % nig) % gsz); u.pn = (wgid % nig) / gsz; if (rev) u.pm = nM - 1 - u.pm; return true;
.LBB0_378:
	s_or_b64 exec, exec, s[14:15]
	s_xor_b64 s[0:1], s[10:11], -1
	v_writelane_b32 v250, s0, 34
	s_movk_i32 s40, 0xb00
	s_waitcnt lgkmcnt(0)
	v_writelane_b32 v250, s1, 35
	s_movk_i32 s0, 0x400
	s_barrier
	s_ashr_i32 s1, s0, 31
	s_lshr_b32 s1, s1, 24
	s_add_i32 s0, s0, s1
	s_ashr_i32 s42, s0, 8
	s_lshl_b32 s10, s42, 7
	v_mov_b32_e32 v14, v158
	v_lshrrev_b32_e32 v241, 2, v158
	v_lshlrev_b32_e32 v241, 11, v241
	v_and_b32_e32 v242, 3, v158
	v_lshl_or_b32 v241, v242, 7, v241
	v_add_u32_e32 v242, 0x40000, v241
	s_cmp_lt_i32 s2, s10
	s_cselect_b64 s[18:19], -1, 0
	s_cmp_ge_i32 s2, s10
	v_readfirstlane_b32 s11, v14
	s_cbranch_scc1 .LBB0_380
	s_lshl_b32 s0, s42, 3
	s_abs_i32 s1, s0
	v_cvt_f32_u32_e32 v0, s1
	s_lshl_b32 s6, s42, 4
	v_readlane_b32 s7, v251, 60
	s_or_b32 s6, s6, s7
	v_rcp_iflag_f32_e32 v0, v0
	v_readlane_b32 s7, v251, 15
	s_mul_i32 s6, s6, s7
	s_sub_i32 s7, 0, s1
	v_mul_f32_e32 v0, 0x4f7ffffe, v0
	v_cvt_u32_f32_e32 v0, v0
	v_readlane_b32 s8, v251, 14
	s_add_i32 s6, s6, s8
	s_abs_i32 s9, s6
	v_readfirstlane_b32 s14, v0
	s_mul_i32 s7, s7, s14
	s_mul_hi_u32 s7, s14, s7
	s_add_i32 s14, s14, s7
	s_mul_hi_u32 s7, s9, s14
	s_mul_i32 s14, s7, s1
	s_xor_b32 s8, s6, s0
	s_sub_i32 s9, s9, s14
	s_ashr_i32 s8, s8, 31
	s_add_i32 s15, s7, 1
	s_sub_i32 s14, s9, s1
	s_cmp_ge_u32 s9, s1
	s_cselect_b32 s7, s15, s7
	s_cselect_b32 s9, s14, s9
	s_add_i32 s14, s7, 1
	s_cmp_ge_u32 s9, s1
	s_cselect_b32 s1, s14, s7
	s_xor_b32 s1, s1, s8
	s_sub_i32 s1, s1, s8
	s_lshl_b32 s7, s1, 3
	s_sub_i32 s8, 0x80, s7
	s_min_i32 s8, s8, 8
	s_abs_i32 s9, s8
	v_cvt_f32_u32_e32 v0, s9
	s_sub_i32 s14, 0, s9
	s_mul_i32 s1, s1, s0
	s_sub_i32 s0, s6, s1
	v_rcp_iflag_f32_e32 v0, v0
	s_abs_i32 s1, s0
	s_xor_b32 s6, s0, s8
	s_ashr_i32 s6, s6, 31
	v_mul_f32_e32 v0, 0x4f7ffffe, v0
	v_cvt_u32_f32_e32 v0, v0
	s_nop 0
	v_readfirstlane_b32 s15, v0
	s_mul_i32 s14, s14, s15
	s_mul_hi_u32 s14, s15, s14
	s_add_i32 s15, s15, s14
	s_mul_hi_u32 s14, s1, s15
	s_mul_i32 s15, s14, s9
	s_sub_i32 s1, s1, s15
	s_add_i32 s20, s14, 1
	s_sub_i32 s15, s1, s9
	s_cmp_ge_u32 s1, s9
	s_cselect_b32 s14, s20, s14
	s_cselect_b32 s1, s15, s1
	s_add_i32 s15, s14, 1
	s_cmp_ge_u32 s1, s9
	s_cselect_b32 s1, s15, s14
	s_xor_b32 s1, s1, s6
	s_sub_i32 s14, s1, s6
	s_mul_i32 s1, s14, s8
	s_sub_i32 s0, s0, s1
	s_add_i32 s15, s0, s7

; #define PG8_STAGE(bufoff, gbase, voff) do { _Pragma("unroll") for (int _i = 0; _i < 2; ++_i) \
;         __builtin_amdgcn_global_load_lds((const unsigned*)((const char*)(gbase) + (voff)[_i]), (PG8_LAS unsigned*)(lds + (bufoff) + ldsw + _i * 8192), 16, 0, 0); } while (0)
; #define PG8_LDA(dst, b, h) do { _Pragma("unroll") for (int m = 0; m < 4; ++m) _Pragma("unroll") for (int k = 0; k < 2; ++k) dst[m][k] = *(const PG8_LAS bf16x8*)(lds + PG8_SA(b, h) + aoff + m * 2048 + k * 1024); } while (0)
; #define PG8_LDB(dst, b, h) do { _Pragma("unroll") for (int n = 0; n < 2; ++n) _Pragma("unroll") for (int k = 0; k < 2; ++k) dst[n][k] = *(const PG8_LAS bf16x8*)(lds + PG8_SB(b, h) + boff + n * 2048 + k * 1024); } while (0)
; #define PG8_MMA(ai, bj, At, Bt) do { __builtin_amdgcn_s_setprio(1); _Pragma("unroll") for (int m = 0; m < 4; ++m) _Pragma("unroll") for (int n = 0; n < 2; ++n) _Pragma("unroll") for (int k = 0; k < 2; ++k) \
;         acc[ai][bj][m][n] = __builtin_amdgcn_mfma_f32_16x16x32_bf16(Bt[n][k], At[m][k], acc[ai][bj][m][n], 0, 0, 0); __builtin_amdgcn_s_setprio(0); } while (0)
; #define PG8_WAIT_V(n) asm volatile("s_waitcnt vmcnt(" #n ")" ::: "memory")
; #define PG8_WAIT_L(n) asm volatile("s_waitcnt lgkmcnt(" #n ")" ::: "memory")
; #define PG8_BAR __builtin_amdgcn_s_barrier()
; #define PG8_SCHED __builtin_amdgcn_sched_barrier(0)
; template <class Epi, class Sched, bool ALIGN_EPI = false, bool SP2 = false>
; __device__ __forceinline__ void gemm_phase(PG8_LAS unsigned char* lds, const Gemm g, const Sched& S, const Epi& E) {
;     ...
;             PG8_LDB(B0, 0, 0); PG8_LDB(B1, 0, 1); PG8_SCHED; PG8_LDA(At, 0, 0); PG8_STAGE(PG8_SA(1, 1), a1 + hstep, voffA);
;             PG8_WAIT_V(8); PG8_WAIT_L(0); PG8_BAR; PG8_MMA(0, 0, At, B0); PG8_MMA(0, 1, At, B1); PG8_BAR; PG8_SCHED;
;             PG8_LDA(At, 0, 1); PG8_STAGE(PG8_SB(0, 0), b2, voffB); PG8_STAGE(PG8_SB(0, 1), b2 + hstep, voffB); PG8_STAGE(PG8_SA(0, 0), a2, voffA);
;             PG8_WAIT_V(8); PG8_WAIT_L(0); PG8_BAR; PG8_MMA(1, 0, At, B0); PG8_MMA(1, 1, At, B1); PG8_BAR; PG8_SCHED;
.LBB0_394:
	s_add_i32 s59, s58, 2
	s_add_u32 s60, s90, 0x80
	s_addc_u32 s61, s91, 0
	s_add_i32 s62, 0, 0x10000
	s_cmp_eq_u32 s35, s58
	s_cselect_b32 s71, s45, s61
	s_cselect_b32 s70, s44, s60
	s_cselect_b32 s61, s81, s57
	s_cselect_b32 s60, s80, s56
	s_add_i32 s58, 0, 0x14000
	v_add_u32_e32 v148, s62, v170
	v_add_u32_e32 v156, s58, v170
	ds_read_b128 v[136:139], v148
	ds_read_b128 v[140:143], v148 offset:1024
	ds_read_b128 v[144:147], v148 offset:2048
	ds_read_b128 v[148:151], v148 offset:3072
	ds_read_b128 v[152:155], v156
	ds_read_b128 v[174:177], v156 offset:1024
	ds_read_b128 v[178:181], v156 offset:2048
	ds_read_b128 v[182:185], v156 offset:3072
	v_lshl_add_u64 v[156:157], s[90:91], 0, v[132:133]
	s_add_i32 m0, s7, 0xc000
	ds_read_b128 v[186:189], v173
	ds_read_b128 v[190:193], v173 offset:1024
	ds_read_b128 v[194:197], v173 offset:2048
	ds_read_b128 v[198:201], v173 offset:3072
	ds_read_b128 v[202:205], v173 offset:4096
	ds_read_b128 v[210:213], v173 offset:5120
	ds_read_b128 v[214:217], v173 offset:6144
	ds_read_b128 v[218:221], v173 offset:7168
	global_load_lds_dwordx4 v[156:157], off
	v_lshl_add_u64 v[156:157], s[90:91], 0, v[134:135]
	s_add_i32 m0, s7, 0xe000
	s_nop 0
	global_load_lds_dwordx4 v[156:157], off
	s_waitcnt vmcnt(8)
	s_waitcnt lgkmcnt(0)
	s_barrier
	s_setprio 1
	s_waitcnt lgkmcnt(0)
	v_mfma_f32_16x16x32_bf16 v[126:129], v[136:139], v[186:189], v[126:129]
	v_mfma_f32_16x16x32_bf16 v[122:125], v[144:147], v[186:189], v[122:125]
	v_mfma_f32_16x16x32_bf16 v[110:113], v[136:139], v[194:197], v[110:113]
	v_mfma_f32_16x16x32_bf16 v[106:109], v[144:147], v[194:197], v[106:109]
	v_mfma_f32_16x16x32_bf16 v[94:97], v[136:139], v[202:205], v[94:97]
	v_mfma_f32_16x16x32_bf16 v[90:93], v[144:147], v[202:205], v[90:93]
	v_mfma_f32_16x16x32_bf16 v[78:81], v[136:139], v[214:217], v[78:81]
	v_mfma_f32_16x16x32_bf16 v[74:77], v[144:147], v[214:217], v[74:77]
	v_mfma_f32_16x16x32_bf16 v[126:129], v[140:143], v[190:193], v[126:129]
	v_mfma_f32_16x16x32_bf16 v[122:125], v[148:151], v[190:193], v[122:125]
	v_mfma_f32_16x16x32_bf16 v[110:113], v[140:143], v[198:201], v[110:113]
	v_mfma_f32_16x16x32_bf16 v[106:109], v[148:151], v[198:201], v[106:109]
	v_mfma_f32_16x16x32_bf16 v[94:97], v[140:143], v[210:213], v[94:97]
	v_mfma_f32_16x16x32_bf16 v[90:93], v[148:151], v[210:213], v[90:93]
	v_mfma_f32_16x16x32_bf16 v[78:81], v[140:143], v[218:221], v[78:81]
	v_mfma_f32_16x16x32_bf16 v[74:77], v[148:151], v[218:221], v[74:77]
	s_setprio 0
	s_setprio 1
	v_mfma_f32_16x16x32_bf16 v[118:121], v[152:155], v[186:189], v[118:121]
	v_mfma_f32_16x16x32_bf16 v[114:117], v[178:181], v[186:189], v[114:117]
	v_mfma_f32_16x16x32_bf16 v[102:105], v[152:155], v[194:197], v[102:105]
	v_mfma_f32_16x16x32_bf16 v[98:101], v[178:181], v[194:197], v[98:101]
	v_mfma_f32_16x16x32_bf16 v[86:89], v[152:155], v[202:205], v[86:89]
	v_mfma_f32_16x16x32_bf16 v[82:85], v[178:181], v[202:205], v[82:85]
	v_mfma_f32_16x16x32_bf16 v[70:73], v[152:155], v[214:217], v[70:73]
	v_mfma_f32_16x16x32_bf16 v[66:69], v[178:181], v[214:217], v[66:69]
	v_mfma_f32_16x16x32_bf16 v[118:121], v[174:177], v[190:193], v[118:121]
	v_mfma_f32_16x16x32_bf16 v[114:117], v[182:185], v[190:193], v[114:117]
	v_mfma_f32_16x16x32_bf16 v[102:105], v[174:177], v[198:201], v[102:105]
	v_mfma_f32_16x16x32_bf16 v[98:101], v[182:185], v[198:201], v[98:101]
	v_mfma_f32_16x16x32_bf16 v[86:89], v[174:177], v[210:213], v[86:89]
	v_mfma_f32_16x16x32_bf16 v[82:85], v[182:185], v[210:213], v[82:85]
	v_mfma_f32_16x16x32_bf16 v[70:73], v[174:177], v[218:221], v[70:73]
	v_mfma_f32_16x16x32_bf16 v[66:69], v[182:185], v[218:221], v[66:69]
	s_setprio 0
	s_barrier
	s_add_i32 s62, s62, s6
	v_lshl_add_u64 v[156:157], s[60:61], 0, v[0:1]
	s_mov_b32 m0, s62
	ds_read_b128 v[186:189], v173 offset:16384
	ds_read_b128 v[190:193], v173 offset:17408
	ds_read_b128 v[194:197], v173 offset:18432
	ds_read_b128 v[198:201], v173 offset:19456
	ds_read_b128 v[202:205], v173 offset:20480
	ds_read_b128 v[210:213], v173 offset:21504
	ds_read_b128 v[214:217], v173 offset:22528
	ds_read_b128 v[218:221], v173 offset:23552
	global_load_lds_dwordx4 v[156:157], off
	s_add_i32 m0, s62, 0x2000
	v_lshl_add_u64 v[168:169], s[60:61], 0, v[130:131]
	s_add_u32 s60, s60, s18
	s_addc_u32 s61, s61, s19
	s_add_i32 s58, s58, s6
	global_load_lds_dwordx4 v[168:169], off
	v_lshl_add_u64 v[206:207], s[60:61], 0, v[0:1]
	s_mov_b32 m0, s58
	v_lshl_add_u64 v[222:223], s[60:61], 0, v[130:131]
	global_load_lds_dwordx4 v[206:207], off
	s_add_i32 m0, s58, 0x2000
	v_lshl_add_u64 v[224:225], s[70:71], 0, v[0:1]
	global_load_lds_dwordx4 v[222:223], off
	s_mov_b32 m0, s7
	v_lshl_add_u64 v[226:227], s[70:71], 0, v[130:131]
	global_load_lds_dwordx4 v[224:225], off
	s_mov_b32 m0, s8
	s_nop 0
	global_load_lds_dwordx4 v[226:227], off
	s_waitcnt vmcnt(8)
	s_waitcnt lgkmcnt(0)
	s_barrier
; #define PG8_STAGE(bufoff, gbase, voff) do { _Pragma("unroll") for (int _i = 0; _i < 2; ++_i) \
;         __builtin_amdgcn_global_load_lds((const unsigned*)((const char*)(gbase) + (voff)[_i]), (PG8_LAS unsigned*)(lds + (bufoff) + ldsw + _i * 8192), 16, 0, 0); } while (0)
; #define PG8_LDA(dst, b, h) do { _Pragma("unroll") for (int m = 0; m < 4; ++m) _Pragma("unroll") for (int k = 0; k < 2; ++k) dst[m][k] = *(const PG8_LAS bf16x8*)(lds + PG8_SA(b, h) + aoff + m * 2048 + k * 1024); } while (0)
; #define PG8_LDB(dst, b, h) do { _Pragma("unroll") for (int n = 0; n < 2; ++n) _Pragma("unroll") for (int k = 0; k < 2; ++k) dst[n][k] = *(const PG8_LAS bf16x8*)(lds + PG8_SB(b, h) + boff + n * 2048 + k * 1024); } while (0)
; #define PG8_MMA(ai, bj, At, Bt) do { __builtin_amdgcn_s_setprio(1); _Pragma("unroll") for (int m = 0; m < 4; ++m) _Pragma("unroll") for (int n = 0; n < 2; ++n) _Pragma("unroll") for (int k = 0; k < 2; ++k) \
;         acc[ai][bj][m][n] = __builtin_amdgcn_mfma_f32_16x16x32_bf16(Bt[n][k], At[m][k], acc[ai][bj][m][n], 0, 0, 0); __builtin_amdgcn_s_setprio(0); } while (0)
; #define PG8_WAIT_V(n) asm volatile("s_waitcnt vmcnt(" #n ")" ::: "memory")
; #define PG8_WAIT_L(n) asm volatile("s_waitcnt lgkmcnt(" #n ")" ::: "memory")
; #define PG8_BAR __builtin_amdgcn_s_barrier()
; #define PG8_SCHED __builtin_amdgcn_sched_barrier(0)
; template <class Epi, class Sched, bool ALIGN_EPI = false, bool SP2 = false>
; __device__ __forceinline__ void gemm_phase(PG8_LAS unsigned char* lds, const Gemm g, const Sched& S, const Epi& E) {
;     ...
;             PG8_WAIT_V(8); PG8_WAIT_L(0); PG8_BAR; PG8_MMA(1, 0, At, B0); PG8_MMA(1, 1, At, B1); PG8_BAR; PG8_SCHED;
;             PG8_LDB(B0, 1, 0); PG8_LDB(B1, 1, 1); PG8_SCHED; PG8_LDA(At, 1, 0); PG8_STAGE(PG8_SA(0, 1), a2 + hstep, voffA);
;             PG8_WAIT_V(8); PG8_WAIT_L(0); PG8_BAR; PG8_MMA(0, 0, At, B0); PG8_MMA(0, 1, At, B1); PG8_BAR; PG8_SCHED;
	s_setprio 1
	s_waitcnt lgkmcnt(0)
	v_mfma_f32_16x16x32_bf16 v[62:65], v[136:139], v[186:189], v[62:65]
	v_mfma_f32_16x16x32_bf16 v[58:61], v[144:147], v[186:189], v[58:61]
	v_mfma_f32_16x16x32_bf16 v[46:49], v[136:139], v[194:197], v[46:49]
	v_mfma_f32_16x16x32_bf16 v[42:45], v[144:147], v[194:197], v[42:45]
	v_mfma_f32_16x16x32_bf16 v[30:33], v[136:139], v[202:205], v[30:33]
	v_mfma_f32_16x16x32_bf16 v[26:29], v[144:147], v[202:205], v[26:29]
	v_mfma_f32_16x16x32_bf16 v[14:17], v[136:139], v[214:217], v[14:17]
	v_mfma_f32_16x16x32_bf16 v[10:13], v[144:147], v[214:217], v[10:13]
	v_mfma_f32_16x16x32_bf16 v[62:65], v[140:143], v[190:193], v[62:65]
	v_mfma_f32_16x16x32_bf16 v[58:61], v[148:151], v[190:193], v[58:61]
	v_mfma_f32_16x16x32_bf16 v[46:49], v[140:143], v[198:201], v[46:49]
	v_mfma_f32_16x16x32_bf16 v[42:45], v[148:151], v[198:201], v[42:45]
	v_mfma_f32_16x16x32_bf16 v[30:33], v[140:143], v[210:213], v[30:33]
	v_mfma_f32_16x16x32_bf16 v[26:29], v[148:151], v[210:213], v[26:29]
	v_mfma_f32_16x16x32_bf16 v[14:17], v[140:143], v[218:221], v[14:17]
	v_mfma_f32_16x16x32_bf16 v[10:13], v[148:151], v[218:221], v[10:13]
	s_setprio 0
	s_setprio 1
	v_mfma_f32_16x16x32_bf16 v[54:57], v[152:155], v[186:189], v[54:57]
	v_mfma_f32_16x16x32_bf16 v[50:53], v[178:181], v[186:189], v[50:53]
	v_mfma_f32_16x16x32_bf16 v[38:41], v[152:155], v[194:197], v[38:41]
	v_mfma_f32_16x16x32_bf16 v[34:37], v[178:181], v[194:197], v[34:37]
	v_mfma_f32_16x16x32_bf16 v[22:25], v[152:155], v[202:205], v[22:25]
	v_mfma_f32_16x16x32_bf16 v[18:21], v[178:181], v[202:205], v[18:21]
	v_mfma_f32_16x16x32_bf16 v[6:9], v[152:155], v[214:217], v[6:9]
	v_mfma_f32_16x16x32_bf16 v[2:5], v[178:181], v[214:217], v[2:5]
	v_mfma_f32_16x16x32_bf16 v[54:57], v[174:177], v[190:193], v[54:57]
	v_mfma_f32_16x16x32_bf16 v[50:53], v[182:185], v[190:193], v[50:53]
	v_mfma_f32_16x16x32_bf16 v[38:41], v[174:177], v[198:201], v[38:41]
	v_mfma_f32_16x16x32_bf16 v[34:37], v[182:185], v[198:201], v[34:37]
	v_mfma_f32_16x16x32_bf16 v[22:25], v[174:177], v[210:213], v[22:25]
	v_mfma_f32_16x16x32_bf16 v[18:21], v[182:185], v[210:213], v[18:21]
	v_mfma_f32_16x16x32_bf16 v[6:9], v[174:177], v[218:221], v[6:9]
	v_mfma_f32_16x16x32_bf16 v[2:5], v[182:185], v[218:221], v[2:5]
	s_setprio 0
	s_barrier
	s_add_i32 s58, 0, 0x18000
	s_add_i32 s62, 0, 0x1c000
	v_add_u32_e32 v148, s58, v170
	v_add_u32_e32 v182, s62, v170
	ds_read_b128 v[136:139], v148
	ds_read_b128 v[140:143], v148 offset:1024
	ds_read_b128 v[144:147], v148 offset:2048
	ds_read_b128 v[148:151], v148 offset:3072
	ds_read_b128 v[152:155], v182
	ds_read_b128 v[174:177], v182 offset:1024
	ds_read_b128 v[178:181], v182 offset:2048
	ds_read_b128 v[182:185], v182 offset:3072
	s_add_u32 s60, s70, s18
	s_addc_u32 s61, s71, s19
	s_mov_b32 m0, s9
	v_lshl_add_u64 v[238:239], s[60:61], 0, v[0:1]
	ds_read_b128 v[186:189], v173 offset:32768
	ds_read_b128 v[190:193], v173 offset:33792
	ds_read_b128 v[194:197], v173 offset:34816
	ds_read_b128 v[198:201], v173 offset:35840
	ds_read_b128 v[202:205], v173 offset:36864
	ds_read_b128 v[210:213], v173 offset:37888
	ds_read_b128 v[214:217], v173 offset:38912
	ds_read_b128 v[218:221], v173 offset:39936
	global_load_lds_dwordx4 v[238:239], off
	v_lshl_add_u64 v[238:239], s[60:61], 0, v[130:131]
	s_mov_b32 m0, s30
	s_nop 0
	global_load_lds_dwordx4 v[238:239], off
	s_waitcnt vmcnt(8)
	s_waitcnt lgkmcnt(0)
	s_barrier
	s_setprio 1
	s_waitcnt lgkmcnt(0)
	v_mfma_f32_16x16x32_bf16 v[126:129], v[136:139], v[186:189], v[126:129]
	v_mfma_f32_16x16x32_bf16 v[122:125], v[144:147], v[186:189], v[122:125]
	v_mfma_f32_16x16x32_bf16 v[110:113], v[136:139], v[194:197], v[110:113]
	v_mfma_f32_16x16x32_bf16 v[106:109], v[144:147], v[194:197], v[106:109]
	v_mfma_f32_16x16x32_bf16 v[94:97], v[136:139], v[202:205], v[94:97]
	v_mfma_f32_16x16x32_bf16 v[90:93], v[144:147], v[202:205], v[90:93]
	v_mfma_f32_16x16x32_bf16 v[78:81], v[136:139], v[214:217], v[78:81]
	v_mfma_f32_16x16x32_bf16 v[74:77], v[144:147], v[214:217], v[74:77]
	v_mfma_f32_16x16x32_bf16 v[126:129], v[140:143], v[190:193], v[126:129]
	v_mfma_f32_16x16x32_bf16 v[122:125], v[148:151], v[190:193], v[122:125]
	v_mfma_f32_16x16x32_bf16 v[110:113], v[140:143], v[198:201], v[110:113]
	v_mfma_f32_16x16x32_bf16 v[106:109], v[148:151], v[198:201], v[106:109]
	v_mfma_f32_16x16x32_bf16 v[94:97], v[140:143], v[210:213], v[94:97]
	v_mfma_f32_16x16x32_bf16 v[90:93], v[148:151], v[210:213], v[90:93]
	v_mfma_f32_16x16x32_bf16 v[78:81], v[140:143], v[218:221], v[78:81]
	v_mfma_f32_16x16x32_bf16 v[74:77], v[148:151], v[218:221], v[74:77]
	s_setprio 0
	s_setprio 1
	v_mfma_f32_16x16x32_bf16 v[118:121], v[152:155], v[186:189], v[118:121]
	v_mfma_f32_16x16x32_bf16 v[114:117], v[178:181], v[186:189], v[114:117]
	v_mfma_f32_16x16x32_bf16 v[102:105], v[152:155], v[194:197], v[102:105]
	v_mfma_f32_16x16x32_bf16 v[98:101], v[178:181], v[194:197], v[98:101]
	v_mfma_f32_16x16x32_bf16 v[86:89], v[152:155], v[202:205], v[86:89]
	v_mfma_f32_16x16x32_bf16 v[82:85], v[178:181], v[202:205], v[82:85]
	v_mfma_f32_16x16x32_bf16 v[70:73], v[152:155], v[214:217], v[70:73]
	v_mfma_f32_16x16x32_bf16 v[66:69], v[178:181], v[214:217], v[66:69]
	v_mfma_f32_16x16x32_bf16 v[118:121], v[174:177], v[190:193], v[118:121]
	v_mfma_f32_16x16x32_bf16 v[114:117], v[182:185], v[190:193], v[114:117]
	v_mfma_f32_16x16x32_bf16 v[102:105], v[174:177], v[198:201], v[102:105]
	v_mfma_f32_16x16x32_bf16 v[98:101], v[182:185], v[198:201], v[98:101]
	v_mfma_f32_16x16x32_bf16 v[86:89], v[174:177], v[210:213], v[86:89]
	v_mfma_f32_16x16x32_bf16 v[82:85], v[182:185], v[210:213], v[82:85]
	v_mfma_f32_16x16x32_bf16 v[70:73], v[174:177], v[218:221], v[70:73]
	v_mfma_f32_16x16x32_bf16 v[66:69], v[182:185], v[218:221], v[66:69]
	s_setprio 0
	s_barrier
; #define PG8_STAGE(bufoff, gbase, voff) do { _Pragma("unroll") for (int _i = 0; _i < 2; ++_i) \
;         __builtin_amdgcn_global_load_lds((const unsigned*)((const char*)(gbase) + (voff)[_i]), (PG8_LAS unsigned*)(lds + (bufoff) + ldsw + _i * 8192), 16, 0, 0); } while (0)
; #define PG8_LDA(dst, b, h) do { _Pragma("unroll") for (int m = 0; m < 4; ++m) _Pragma("unroll") for (int k = 0; k < 2; ++k) dst[m][k] = *(const PG8_LAS bf16x8*)(lds + PG8_SA(b, h) + aoff + m * 2048 + k * 1024); } while (0)
; #define PG8_MMA(ai, bj, At, Bt) do { __builtin_amdgcn_s_setprio(1); _Pragma("unroll") for (int m = 0; m < 4; ++m) _Pragma("unroll") for (int n = 0; n < 2; ++n) _Pragma("unroll") for (int k = 0; k < 2; ++k) \
;         acc[ai][bj][m][n] = __builtin_amdgcn_mfma_f32_16x16x32_bf16(Bt[n][k], At[m][k], acc[ai][bj][m][n], 0, 0, 0); __builtin_amdgcn_s_setprio(0); } while (0)
; #define PG8_WAIT_V(n) asm volatile("s_waitcnt vmcnt(" #n ")" ::: "memory")
; #define PG8_WAIT_L(n) asm volatile("s_waitcnt lgkmcnt(" #n ")" ::: "memory")
; #define PG8_BAR __builtin_amdgcn_s_barrier()
; #define PG8_SCHED __builtin_amdgcn_sched_barrier(0)
; template <class Epi, class Sched, bool ALIGN_EPI = false, bool SP2 = false>
; __device__ __forceinline__ void gemm_phase(PG8_LAS unsigned char* lds, const Gemm g, const Sched& S, const Epi& E) {
;     ...
;             PG8_LDA(At, 1, 1); PG8_STAGE(PG8_SB(1, 0), b3, voffB); PG8_STAGE(PG8_SB(1, 1), b3 + hstep, voffB); PG8_STAGE(PG8_SA(1, 0), a3, voffA);
;             PG8_WAIT_V(8); PG8_WAIT_L(0); PG8_BAR; PG8_MMA(1, 0, At, B0); PG8_MMA(1, 1, At, B1); PG8_BAR; PG8_SCHED;
;     __device__ __forceinline__ void operator()(const f32x4 (&acc)[2][2][4][2], const Unit& u, int wr, int wc, int fr, int fq) const {
;     ...
;             for (int gg = 0; gg < 4; ++gg) { const int g = hb * 4 + gg; const size_t offn = (size_t)(row0 + (g >> 2) * 128 + (g & 3) * 16) * D + col0;
; #pragma unroll
;                 for (int k = 0; k < 4; ++k) rin[gg][k] = *(const u32x2v*)(in + offn + (k >> 1) * 128 + (k & 1) * 16); }
	s_add_i32 s58, s58, s6
	v_lshl_add_u64 v[156:157], v[156:157], 0, s[22:23]
	s_mov_b32 m0, s58
	ds_read_b128 v[186:189], v173 offset:49152
	ds_read_b128 v[190:193], v173 offset:50176
	ds_read_b128 v[194:197], v173 offset:51200
	ds_read_b128 v[198:201], v173 offset:52224
	ds_read_b128 v[202:205], v173 offset:53248
	ds_read_b128 v[210:213], v173 offset:54272
	ds_read_b128 v[214:217], v173 offset:55296
	ds_read_b128 v[218:221], v173 offset:56320
	global_load_lds_dwordx4 v[156:157], off
	v_lshl_add_u64 v[156:157], v[168:169], 0, s[22:23]
	s_add_i32 m0, s58, 0x2000
	s_add_i32 s58, s62, s6
	global_load_lds_dwordx4 v[156:157], off
	v_lshl_add_u64 v[156:157], v[206:207], 0, s[22:23]
	s_mov_b32 m0, s58
	s_nop 0
	global_load_lds_dwordx4 v[156:157], off
	v_lshl_add_u64 v[156:157], v[222:223], 0, s[22:23]
	s_add_i32 m0, s58, 0x2000
	s_nop 0
	global_load_lds_dwordx4 v[156:157], off
	v_lshl_add_u64 v[156:157], v[224:225], 0, s[22:23]
	s_mov_b32 m0, s33
	s_nop 0
	global_load_lds_dwordx4 v[156:157], off
	v_lshl_add_u64 v[156:157], v[226:227], 0, s[22:23]
	s_mov_b32 m0, s34
	s_nop 0
	global_load_lds_dwordx4 v[156:157], off
	s_waitcnt vmcnt(8)
	s_waitcnt lgkmcnt(0)
	s_barrier
	s_setprio 1
	s_waitcnt lgkmcnt(0)
	v_mfma_f32_16x16x32_bf16 v[62:65], v[136:139], v[186:189], v[62:65]
	v_mfma_f32_16x16x32_bf16 v[58:61], v[144:147], v[186:189], v[58:61]
	v_mfma_f32_16x16x32_bf16 v[46:49], v[136:139], v[194:197], v[46:49]
	v_mfma_f32_16x16x32_bf16 v[42:45], v[144:147], v[194:197], v[42:45]
	v_mfma_f32_16x16x32_bf16 v[30:33], v[136:139], v[202:205], v[30:33]
	v_mfma_f32_16x16x32_bf16 v[26:29], v[144:147], v[202:205], v[26:29]
	v_mfma_f32_16x16x32_bf16 v[14:17], v[136:139], v[214:217], v[14:17]
	v_mfma_f32_16x16x32_bf16 v[10:13], v[144:147], v[214:217], v[10:13]
	v_mfma_f32_16x16x32_bf16 v[62:65], v[140:143], v[190:193], v[62:65]
	v_mfma_f32_16x16x32_bf16 v[58:61], v[148:151], v[190:193], v[58:61]
	v_mfma_f32_16x16x32_bf16 v[46:49], v[140:143], v[198:201], v[46:49]
	v_mfma_f32_16x16x32_bf16 v[42:45], v[148:151], v[198:201], v[42:45]
	v_mfma_f32_16x16x32_bf16 v[30:33], v[140:143], v[210:213], v[30:33]
	v_mfma_f32_16x16x32_bf16 v[26:29], v[148:151], v[210:213], v[26:29]
	v_mfma_f32_16x16x32_bf16 v[14:17], v[140:143], v[218:221], v[14:17]
	v_mfma_f32_16x16x32_bf16 v[10:13], v[148:151], v[218:221], v[10:13]
	s_setprio 0
	s_setprio 1
	v_mfma_f32_16x16x32_bf16 v[54:57], v[152:155], v[186:189], v[54:57]
	v_mfma_f32_16x16x32_bf16 v[50:53], v[178:181], v[186:189], v[50:53]
	v_mfma_f32_16x16x32_bf16 v[38:41], v[152:155], v[194:197], v[38:41]
	v_mfma_f32_16x16x32_bf16 v[34:37], v[178:181], v[194:197], v[34:37]
	v_mfma_f32_16x16x32_bf16 v[22:25], v[152:155], v[202:205], v[22:25]
	v_mfma_f32_16x16x32_bf16 v[18:21], v[178:181], v[202:205], v[18:21]
	v_mfma_f32_16x16x32_bf16 v[6:9], v[152:155], v[214:217], v[6:9]
	v_mfma_f32_16x16x32_bf16 v[2:5], v[178:181], v[214:217], v[2:5]
	v_mfma_f32_16x16x32_bf16 v[54:57], v[174:177], v[190:193], v[54:57]
	v_mfma_f32_16x16x32_bf16 v[50:53], v[182:185], v[190:193], v[50:53]
	v_mfma_f32_16x16x32_bf16 v[38:41], v[174:177], v[198:201], v[38:41]
	v_mfma_f32_16x16x32_bf16 v[34:37], v[182:185], v[198:201], v[34:37]
	v_mfma_f32_16x16x32_bf16 v[22:25], v[174:177], v[210:213], v[22:25]
	v_mfma_f32_16x16x32_bf16 v[18:21], v[182:185], v[210:213], v[18:21]
	v_mfma_f32_16x16x32_bf16 v[6:9], v[174:177], v[218:221], v[6:9]
	v_mfma_f32_16x16x32_bf16 v[2:5], v[182:185], v[218:221], v[2:5]
	s_setprio 0
	s_barrier
	s_sub_u32 s100, s31, 6
	s_cmp_eq_u32 s58, s100
	s_cbranch_scc0 .Lpf_d1_a
	s_lshl_b32 s100, s15, 19
	s_lshl_b32 s101, s14, 9
	s_add_u32 s100, s100, s101
	s_add_u32 s100, s100, s12
	s_addc_u32 s101, s13, 0
	global_load_dword v240, v241, s[100:101]
.Lpf_d1_a:
	s_sub_u32 s100, s31, 4
	s_cmp_eq_u32 s58, s100
	s_cbranch_scc0 .Lpf_d1_b
	s_lshl_b32 s100, s15, 19
	s_lshl_b32 s101, s14, 9
	s_add_u32 s100, s100, s101
	s_add_u32 s100, s100, s12
	s_addc_u32 s101, s13, 0
	global_load_dword v240, v242, s[100:101]
.Lpf_d1_b:
	s_add_u32 s90, s90, 0x100
	s_addc_u32 s91, s91, 0
	s_add_u32 s56, s56, 0x100
	s_addc_u32 s57, s57, 0
	s_cmp_ge_i32 s59, s31
	s_mov_b32 s58, s59
	s_cbranch_scc0 .LBB0_394
	v_readlane_b32 s62, v250, 20
	s_mov_b32 s84, s62
	v_readlane_b32 s63, v250, 21

;     __host__ __device__ bool next(int i, Unit& u) const {
;         const long L = (long)i * G + c; if (L >= nwg) return false;
;         int wgid = (int)L; { const int q = nwg / NXCD, r = nwg % NXCD, xcd = wgid % NXCD, off = wgid / NXCD; wgid = (xcd < r ? xcd * (q + 1) : r * (q + 1) + (xcd - r) * q) + off; }
;         const int nig = WGM * nN, gid = wgid / nig, fm = gid * WGM, gsz = (nM - fm) < WGM ? (nM - fm) : WGM;
;         u.pm = fm + ((wgid % nig) % gsz); u.pn = (wgid % nig) / gsz; if (rev) u.pm = nM - 1 - u.pm; return true;
.LBB0_1083:
	s_or_b64 exec, exec, s[10:11]
	s_movk_i32 s38, 0x400
	s_movk_i32 s0, 0x400
	s_waitcnt lgkmcnt(0)
	s_barrier
	s_ashr_i32 s1, s0, 31
	s_lshr_b32 s1, s1, 24
	s_add_i32 s0, s0, s1
	s_ashr_i32 s42, s0, 8
	s_lshl_b32 s10, s42, 7
	s_cmp_lt_i32 s2, s10
	v_mov_b32_e32 v14, v158
	v_lshrrev_b32_e32 v241, 2, v158
	v_lshlrev_b32_e32 v241, 11, v241
	v_and_b32_e32 v242, 3, v158
	v_lshl_or_b32 v241, v242, 7, v241
	v_add_u32_e32 v242, 0x40000, v241
	s_cselect_b64 s[14:15], -1, 0
	s_and_b64 vcc, exec, s[14:15]
	v_readfirstlane_b32 s11, v14
	s_cbranch_vccz .LBB0_1085
	s_lshl_b32 s0, s42, 3
	s_abs_i32 s1, s0
	v_cvt_f32_u32_e32 v0, s1
	s_lshl_b32 s6, s42, 4
	v_readlane_b32 s7, v251, 60
	s_or_b32 s6, s6, s7
	v_rcp_iflag_f32_e32 v0, v0
	v_readlane_b32 s7, v251, 15
	s_mul_i32 s6, s6, s7
	s_sub_i32 s7, 0, s1
	v_mul_f32_e32 v0, 0x4f7ffffe, v0
	v_cvt_u32_f32_e32 v0, v0
	v_readlane_b32 s8, v251, 14
	s_add_i32 s6, s6, s8
	s_abs_i32 s9, s6
	v_readfirstlane_b32 s12, v0
	s_mul_i32 s7, s7, s12
	s_mul_hi_u32 s7, s12, s7
	s_add_i32 s12, s12, s7
	s_mul_hi_u32 s7, s9, s12
	s_mul_i32 s12, s7, s1
	s_xor_b32 s8, s6, s0
	s_sub_i32 s9, s9, s12
	s_ashr_i32 s8, s8, 31
	s_add_i32 s13, s7, 1
	s_sub_i32 s12, s9, s1
	s_cmp_ge_u32 s9, s1
	s_cselect_b32 s7, s13, s7
	s_cselect_b32 s9, s12, s9
	s_add_i32 s12, s7, 1
	s_cmp_ge_u32 s9, s1
	s_cselect_b32 s1, s12, s7
	s_xor_b32 s1, s1, s8
	s_sub_i32 s1, s1, s8
	s_lshl_b32 s7, s1, 3
	s_sub_i32 s8, 0x80, s7
	s_min_i32 s8, s8, 8
	s_abs_i32 s9, s8
	v_cvt_f32_u32_e32 v0, s9
	s_sub_i32 s12, 0, s9
	s_mul_i32 s1, s1, s0
	s_sub_i32 s0, s6, s1
	v_rcp_iflag_f32_e32 v0, v0
	s_abs_i32 s1, s0
	s_xor_b32 s6, s0, s8
	s_ashr_i32 s6, s6, 31
	v_mul_f32_e32 v0, 0x4f7ffffe, v0
	v_cvt_u32_f32_e32 v0, v0
	s_nop 0
	v_readfirstlane_b32 s13, v0
	s_mul_i32 s12, s12, s13
	s_mul_hi_u32 s12, s13, s12
	s_add_i32 s13, s13, s12
	s_mul_hi_u32 s12, s1, s13
	s_mul_i32 s13, s12, s9
	s_sub_i32 s1, s1, s13
	s_add_i32 s18, s12, 1
	s_sub_i32 s13, s1, s9
	s_cmp_ge_u32 s1, s9
	s_cselect_b32 s12, s18, s12
	s_cselect_b32 s1, s13, s1
	s_add_i32 s13, s12, 1
	s_cmp_ge_u32 s1, s9
	s_cselect_b32 s1, s13, s12
	s_xor_b32 s1, s1, s6
	s_sub_i32 s12, s1, s6
	s_mul_i32 s1, s12, s8
	s_sub_i32 s0, s0, s1
	s_add_i32 s13, s0, s7

; #define PG8_STAGE(bufoff, gbase, voff) do { _Pragma("unroll") for (int _i = 0; _i < 2; ++_i) \
;         __builtin_amdgcn_global_load_lds((const unsigned*)((const char*)(gbase) + (voff)[_i]), (PG8_LAS unsigned*)(lds + (bufoff) + ldsw + _i * 8192), 16, 0, 0); } while (0)
; #define PG8_LDA(dst, b, h) do { _Pragma("unroll") for (int m = 0; m < 4; ++m) _Pragma("unroll") for (int k = 0; k < 2; ++k) dst[m][k] = *(const PG8_LAS bf16x8*)(lds + PG8_SA(b, h) + aoff + m * 2048 + k * 1024); } while (0)
; #define PG8_LDB(dst, b, h) do { _Pragma("unroll") for (int n = 0; n < 2; ++n) _Pragma("unroll") for (int k = 0; k < 2; ++k) dst[n][k] = *(const PG8_LAS bf16x8*)(lds + PG8_SB(b, h) + boff + n * 2048 + k * 1024); } while (0)
; #define PG8_MMA(ai, bj, At, Bt) do { __builtin_amdgcn_s_setprio(1); _Pragma("unroll") for (int m = 0; m < 4; ++m) _Pragma("unroll") for (int n = 0; n < 2; ++n) _Pragma("unroll") for (int k = 0; k < 2; ++k) \
;         acc[ai][bj][m][n] = __builtin_amdgcn_mfma_f32_16x16x32_bf16(Bt[n][k], At[m][k], acc[ai][bj][m][n], 0, 0, 0); __builtin_amdgcn_s_setprio(0); } while (0)
; #define PG8_WAIT_V(n) asm volatile("s_waitcnt vmcnt(" #n ")" ::: "memory")
; #define PG8_WAIT_L(n) asm volatile("s_waitcnt lgkmcnt(" #n ")" ::: "memory")
; #define PG8_BAR __builtin_amdgcn_s_barrier()
; #define PG8_SCHED __builtin_amdgcn_sched_barrier(0)
; template <class Epi, class Sched, bool ALIGN_EPI = false, bool SP2 = false>
; __device__ __forceinline__ void gemm_phase(PG8_LAS unsigned char* lds, const Gemm g, const Sched& S, const Epi& E) {
;     ...
;             PG8_LDB(B0, 0, 0); PG8_LDB(B1, 0, 1); PG8_SCHED; PG8_LDA(At, 0, 0); PG8_STAGE(PG8_SA(1, 1), a1 + hstep, voffA);
;             PG8_WAIT_V(8); PG8_WAIT_L(0); PG8_BAR; PG8_MMA(0, 0, At, B0); PG8_MMA(0, 1, At, B1); PG8_BAR; PG8_SCHED;
;             PG8_LDA(At, 0, 1); PG8_STAGE(PG8_SB(0, 0), b2, voffB); PG8_STAGE(PG8_SB(0, 1), b2 + hstep, voffB); PG8_STAGE(PG8_SA(0, 0), a2, voffA);
;             PG8_WAIT_V(8); PG8_WAIT_L(0); PG8_BAR; PG8_MMA(1, 0, At, B0); PG8_MMA(1, 1, At, B1); PG8_BAR; PG8_SCHED;
.LBB0_1099:
	s_add_i32 s59, s58, 2
	s_add_u32 s60, s80, 0x80
	s_addc_u32 s61, s81, 0
	s_add_i32 s62, 0, 0x10000
	s_cmp_eq_u32 s35, s58
	s_cselect_b32 s71, s45, s61
	s_cselect_b32 s70, s44, s60
	s_cselect_b32 s61, s79, s57
	s_cselect_b32 s60, s78, s56
	s_add_i32 s58, 0, 0x14000
	v_add_u32_e32 v148, s62, v169
	v_add_u32_e32 v156, s58, v169
	ds_read_b128 v[136:139], v148
	ds_read_b128 v[140:143], v148 offset:1024
	ds_read_b128 v[144:147], v148 offset:2048
	ds_read_b128 v[148:151], v148 offset:3072
	ds_read_b128 v[152:155], v156
	ds_read_b128 v[174:177], v156 offset:1024
	ds_read_b128 v[178:181], v156 offset:2048
	ds_read_b128 v[182:185], v156 offset:3072
	v_lshl_add_u64 v[156:157], s[80:81], 0, v[132:133]
	s_add_i32 m0, s7, 0xc000
	ds_read_b128 v[186:189], v172
	ds_read_b128 v[190:193], v172 offset:1024
	ds_read_b128 v[194:197], v172 offset:2048
	ds_read_b128 v[198:201], v172 offset:3072
	ds_read_b128 v[202:205], v172 offset:4096
	ds_read_b128 v[210:213], v172 offset:5120
	ds_read_b128 v[214:217], v172 offset:6144
	ds_read_b128 v[218:221], v172 offset:7168
	global_load_lds_dwordx4 v[156:157], off
	v_lshl_add_u64 v[156:157], s[80:81], 0, v[134:135]
	s_add_i32 m0, s7, 0xe000
	s_nop 0
	global_load_lds_dwordx4 v[156:157], off
	s_waitcnt vmcnt(8)
	s_waitcnt lgkmcnt(0)
	s_barrier
	s_setprio 1
	s_waitcnt lgkmcnt(0)
	v_mfma_f32_16x16x32_bf16 v[126:129], v[136:139], v[186:189], v[126:129]
	v_mfma_f32_16x16x32_bf16 v[122:125], v[144:147], v[186:189], v[122:125]
	v_mfma_f32_16x16x32_bf16 v[110:113], v[136:139], v[194:197], v[110:113]
	v_mfma_f32_16x16x32_bf16 v[106:109], v[144:147], v[194:197], v[106:109]
	v_mfma_f32_16x16x32_bf16 v[94:97], v[136:139], v[202:205], v[94:97]
	v_mfma_f32_16x16x32_bf16 v[90:93], v[144:147], v[202:205], v[90:93]
	v_mfma_f32_16x16x32_bf16 v[78:81], v[136:139], v[214:217], v[78:81]
	v_mfma_f32_16x16x32_bf16 v[74:77], v[144:147], v[214:217], v[74:77]
	v_mfma_f32_16x16x32_bf16 v[126:129], v[140:143], v[190:193], v[126:129]
	v_mfma_f32_16x16x32_bf16 v[122:125], v[148:151], v[190:193], v[122:125]
	v_mfma_f32_16x16x32_bf16 v[110:113], v[140:143], v[198:201], v[110:113]
	v_mfma_f32_16x16x32_bf16 v[106:109], v[148:151], v[198:201], v[106:109]
	v_mfma_f32_16x16x32_bf16 v[94:97], v[140:143], v[210:213], v[94:97]
	v_mfma_f32_16x16x32_bf16 v[90:93], v[148:151], v[210:213], v[90:93]
	v_mfma_f32_16x16x32_bf16 v[78:81], v[140:143], v[218:221], v[78:81]
	v_mfma_f32_16x16x32_bf16 v[74:77], v[148:151], v[218:221], v[74:77]
	s_setprio 0
	s_setprio 1
	v_mfma_f32_16x16x32_bf16 v[118:121], v[152:155], v[186:189], v[118:121]
	v_mfma_f32_16x16x32_bf16 v[114:117], v[178:181], v[186:189], v[114:117]
	v_mfma_f32_16x16x32_bf16 v[102:105], v[152:155], v[194:197], v[102:105]
	v_mfma_f32_16x16x32_bf16 v[98:101], v[178:181], v[194:197], v[98:101]
	v_mfma_f32_16x16x32_bf16 v[86:89], v[152:155], v[202:205], v[86:89]
	v_mfma_f32_16x16x32_bf16 v[82:85], v[178:181], v[202:205], v[82:85]
	v_mfma_f32_16x16x32_bf16 v[70:73], v[152:155], v[214:217], v[70:73]
	v_mfma_f32_16x16x32_bf16 v[66:69], v[178:181], v[214:217], v[66:69]
	v_mfma_f32_16x16x32_bf16 v[118:121], v[174:177], v[190:193], v[118:121]
	v_mfma_f32_16x16x32_bf16 v[114:117], v[182:185], v[190:193], v[114:117]
	v_mfma_f32_16x16x32_bf16 v[102:105], v[174:177], v[198:201], v[102:105]
	v_mfma_f32_16x16x32_bf16 v[98:101], v[182:185], v[198:201], v[98:101]
	v_mfma_f32_16x16x32_bf16 v[86:89], v[174:177], v[210:213], v[86:89]
	v_mfma_f32_16x16x32_bf16 v[82:85], v[182:185], v[210:213], v[82:85]
	v_mfma_f32_16x16x32_bf16 v[70:73], v[174:177], v[218:221], v[70:73]
	v_mfma_f32_16x16x32_bf16 v[66:69], v[182:185], v[218:221], v[66:69]
	s_setprio 0
	s_barrier
	s_add_i32 s62, s62, s6
	v_lshl_add_u64 v[156:157], s[60:61], 0, v[0:1]
	s_mov_b32 m0, s62
	ds_read_b128 v[186:189], v172 offset:16384
	ds_read_b128 v[190:193], v172 offset:17408
	ds_read_b128 v[194:197], v172 offset:18432
	ds_read_b128 v[198:201], v172 offset:19456
	ds_read_b128 v[202:205], v172 offset:20480
	ds_read_b128 v[210:213], v172 offset:21504
	ds_read_b128 v[214:217], v172 offset:22528
	ds_read_b128 v[218:221], v172 offset:23552
	global_load_lds_dwordx4 v[156:157], off
	s_add_i32 m0, s62, 0x2000
	v_lshl_add_u64 v[166:167], s[60:61], 0, v[130:131]
	s_add_u32 s60, s60, s14
	s_addc_u32 s61, s61, s15
	s_add_i32 s58, s58, s6
	global_load_lds_dwordx4 v[166:167], off
	v_lshl_add_u64 v[206:207], s[60:61], 0, v[0:1]
	s_mov_b32 m0, s58
	v_lshl_add_u64 v[222:223], s[60:61], 0, v[130:131]
	global_load_lds_dwordx4 v[206:207], off
	s_add_i32 m0, s58, 0x2000
	v_lshl_add_u64 v[224:225], s[70:71], 0, v[0:1]
	global_load_lds_dwordx4 v[222:223], off
	s_mov_b32 m0, s7
	v_lshl_add_u64 v[226:227], s[70:71], 0, v[130:131]
	global_load_lds_dwordx4 v[224:225], off
	s_mov_b32 m0, s8
	s_nop 0
	global_load_lds_dwordx4 v[226:227], off
	s_waitcnt vmcnt(8)
	s_waitcnt lgkmcnt(0)
	s_barrier
; #define PG8_STAGE(bufoff, gbase, voff) do { _Pragma("unroll") for (int _i = 0; _i < 2; ++_i) \
;         __builtin_amdgcn_global_load_lds((const unsigned*)((const char*)(gbase) + (voff)[_i]), (PG8_LAS unsigned*)(lds + (bufoff) + ldsw + _i * 8192), 16, 0, 0); } while (0)
; #define PG8_LDA(dst, b, h) do { _Pragma("unroll") for (int m = 0; m < 4; ++m) _Pragma("unroll") for (int k = 0; k < 2; ++k) dst[m][k] = *(const PG8_LAS bf16x8*)(lds + PG8_SA(b, h) + aoff + m * 2048 + k * 1024); } while (0)
; #define PG8_LDB(dst, b, h) do { _Pragma("unroll") for (int n = 0; n < 2; ++n) _Pragma("unroll") for (int k = 0; k < 2; ++k) dst[n][k] = *(const PG8_LAS bf16x8*)(lds + PG8_SB(b, h) + boff + n * 2048 + k * 1024); } while (0)
; #define PG8_MMA(ai, bj, At, Bt) do { __builtin_amdgcn_s_setprio(1); _Pragma("unroll") for (int m = 0; m < 4; ++m) _Pragma("unroll") for (int n = 0; n < 2; ++n) _Pragma("unroll") for (int k = 0; k < 2; ++k) \
;         acc[ai][bj][m][n] = __builtin_amdgcn_mfma_f32_16x16x32_bf16(Bt[n][k], At[m][k], acc[ai][bj][m][n], 0, 0, 0); __builtin_amdgcn_s_setprio(0); } while (0)
; #define PG8_WAIT_V(n) asm volatile("s_waitcnt vmcnt(" #n ")" ::: "memory")
; #define PG8_WAIT_L(n) asm volatile("s_waitcnt lgkmcnt(" #n ")" ::: "memory")
; #define PG8_BAR __builtin_amdgcn_s_barrier()
; #define PG8_SCHED __builtin_amdgcn_sched_barrier(0)
; template <class Epi, class Sched, bool ALIGN_EPI = false, bool SP2 = false>
; __device__ __forceinline__ void gemm_phase(PG8_LAS unsigned char* lds, const Gemm g, const Sched& S, const Epi& E) {
;     ...
;             PG8_WAIT_V(8); PG8_WAIT_L(0); PG8_BAR; PG8_MMA(1, 0, At, B0); PG8_MMA(1, 1, At, B1); PG8_BAR; PG8_SCHED;
;             PG8_LDB(B0, 1, 0); PG8_LDB(B1, 1, 1); PG8_SCHED; PG8_LDA(At, 1, 0); PG8_STAGE(PG8_SA(0, 1), a2 + hstep, voffA);
;             PG8_WAIT_V(8); PG8_WAIT_L(0); PG8_BAR; PG8_MMA(0, 0, At, B0); PG8_MMA(0, 1, At, B1); PG8_BAR; PG8_SCHED;
	s_setprio 1
	s_waitcnt lgkmcnt(0)
	v_mfma_f32_16x16x32_bf16 v[62:65], v[136:139], v[186:189], v[62:65]
	v_mfma_f32_16x16x32_bf16 v[58:61], v[144:147], v[186:189], v[58:61]
	v_mfma_f32_16x16x32_bf16 v[46:49], v[136:139], v[194:197], v[46:49]
	v_mfma_f32_16x16x32_bf16 v[42:45], v[144:147], v[194:197], v[42:45]
	v_mfma_f32_16x16x32_bf16 v[30:33], v[136:139], v[202:205], v[30:33]
	v_mfma_f32_16x16x32_bf16 v[26:29], v[144:147], v[202:205], v[26:29]
	v_mfma_f32_16x16x32_bf16 v[14:17], v[136:139], v[214:217], v[14:17]
	v_mfma_f32_16x16x32_bf16 v[10:13], v[144:147], v[214:217], v[10:13]
	v_mfma_f32_16x16x32_bf16 v[62:65], v[140:143], v[190:193], v[62:65]
	v_mfma_f32_16x16x32_bf16 v[58:61], v[148:151], v[190:193], v[58:61]
	v_mfma_f32_16x16x32_bf16 v[46:49], v[140:143], v[198:201], v[46:49]
	v_mfma_f32_16x16x32_bf16 v[42:45], v[148:151], v[198:201], v[42:45]
	v_mfma_f32_16x16x32_bf16 v[30:33], v[140:143], v[210:213], v[30:33]
	v_mfma_f32_16x16x32_bf16 v[26:29], v[148:151], v[210:213], v[26:29]
	v_mfma_f32_16x16x32_bf16 v[14:17], v[140:143], v[218:221], v[14:17]
	v_mfma_f32_16x16x32_bf16 v[10:13], v[148:151], v[218:221], v[10:13]
	s_setprio 0
	s_setprio 1
	v_mfma_f32_16x16x32_bf16 v[54:57], v[152:155], v[186:189], v[54:57]
	v_mfma_f32_16x16x32_bf16 v[50:53], v[178:181], v[186:189], v[50:53]
	v_mfma_f32_16x16x32_bf16 v[38:41], v[152:155], v[194:197], v[38:41]
	v_mfma_f32_16x16x32_bf16 v[34:37], v[178:181], v[194:197], v[34:37]
	v_mfma_f32_16x16x32_bf16 v[22:25], v[152:155], v[202:205], v[22:25]
	v_mfma_f32_16x16x32_bf16 v[18:21], v[178:181], v[202:205], v[18:21]
	v_mfma_f32_16x16x32_bf16 v[6:9], v[152:155], v[214:217], v[6:9]
	v_mfma_f32_16x16x32_bf16 v[2:5], v[178:181], v[214:217], v[2:5]
	v_mfma_f32_16x16x32_bf16 v[54:57], v[174:177], v[190:193], v[54:57]
	v_mfma_f32_16x16x32_bf16 v[50:53], v[182:185], v[190:193], v[50:53]
	v_mfma_f32_16x16x32_bf16 v[38:41], v[174:177], v[198:201], v[38:41]
	v_mfma_f32_16x16x32_bf16 v[34:37], v[182:185], v[198:201], v[34:37]
	v_mfma_f32_16x16x32_bf16 v[22:25], v[174:177], v[210:213], v[22:25]
	v_mfma_f32_16x16x32_bf16 v[18:21], v[182:185], v[210:213], v[18:21]
	v_mfma_f32_16x16x32_bf16 v[6:9], v[174:177], v[218:221], v[6:9]
	v_mfma_f32_16x16x32_bf16 v[2:5], v[182:185], v[218:221], v[2:5]
	s_setprio 0
	s_barrier
	s_add_i32 s58, 0, 0x18000
	s_add_i32 s62, 0, 0x1c000
	v_add_u32_e32 v148, s58, v169
	v_add_u32_e32 v173, s62, v169
	ds_read_b128 v[136:139], v148
	ds_read_b128 v[140:143], v148 offset:1024
	ds_read_b128 v[144:147], v148 offset:2048
	ds_read_b128 v[148:151], v148 offset:3072
	ds_read_b128 v[152:155], v173
	ds_read_b128 v[174:177], v173 offset:1024
	ds_read_b128 v[178:181], v173 offset:2048
	ds_read_b128 v[182:185], v173 offset:3072
	s_add_u32 s60, s70, s14
	s_addc_u32 s61, s71, s15
	s_mov_b32 m0, s9
	v_lshl_add_u64 v[238:239], s[60:61], 0, v[0:1]
	ds_read_b128 v[186:189], v172 offset:32768
	ds_read_b128 v[190:193], v172 offset:33792
	ds_read_b128 v[194:197], v172 offset:34816
	ds_read_b128 v[198:201], v172 offset:35840
	ds_read_b128 v[202:205], v172 offset:36864
	ds_read_b128 v[210:213], v172 offset:37888
	ds_read_b128 v[214:217], v172 offset:38912
	ds_read_b128 v[218:221], v172 offset:39936
	global_load_lds_dwordx4 v[238:239], off
	v_lshl_add_u64 v[238:239], s[60:61], 0, v[130:131]
	s_mov_b32 m0, s30
	s_nop 0
	global_load_lds_dwordx4 v[238:239], off
	s_waitcnt vmcnt(8)
	s_waitcnt lgkmcnt(0)
	s_barrier
	s_setprio 1
	s_waitcnt lgkmcnt(0)
	v_mfma_f32_16x16x32_bf16 v[126:129], v[136:139], v[186:189], v[126:129]
	v_mfma_f32_16x16x32_bf16 v[122:125], v[144:147], v[186:189], v[122:125]
	v_mfma_f32_16x16x32_bf16 v[110:113], v[136:139], v[194:197], v[110:113]
	v_mfma_f32_16x16x32_bf16 v[106:109], v[144:147], v[194:197], v[106:109]
	v_mfma_f32_16x16x32_bf16 v[94:97], v[136:139], v[202:205], v[94:97]
	v_mfma_f32_16x16x32_bf16 v[90:93], v[144:147], v[202:205], v[90:93]
	v_mfma_f32_16x16x32_bf16 v[78:81], v[136:139], v[214:217], v[78:81]
	v_mfma_f32_16x16x32_bf16 v[74:77], v[144:147], v[214:217], v[74:77]
	v_mfma_f32_16x16x32_bf16 v[126:129], v[140:143], v[190:193], v[126:129]
	v_mfma_f32_16x16x32_bf16 v[122:125], v[148:151], v[190:193], v[122:125]
	v_mfma_f32_16x16x32_bf16 v[110:113], v[140:143], v[198:201], v[110:113]
	v_mfma_f32_16x16x32_bf16 v[106:109], v[148:151], v[198:201], v[106:109]
	v_mfma_f32_16x16x32_bf16 v[94:97], v[140:143], v[210:213], v[94:97]
	v_mfma_f32_16x16x32_bf16 v[90:93], v[148:151], v[210:213], v[90:93]
	v_mfma_f32_16x16x32_bf16 v[78:81], v[140:143], v[218:221], v[78:81]
	v_mfma_f32_16x16x32_bf16 v[74:77], v[148:151], v[218:221], v[74:77]
	s_setprio 0
	s_setprio 1
	v_mfma_f32_16x16x32_bf16 v[118:121], v[152:155], v[186:189], v[118:121]
	v_mfma_f32_16x16x32_bf16 v[114:117], v[178:181], v[186:189], v[114:117]
	v_mfma_f32_16x16x32_bf16 v[102:105], v[152:155], v[194:197], v[102:105]
	v_mfma_f32_16x16x32_bf16 v[98:101], v[178:181], v[194:197], v[98:101]
	v_mfma_f32_16x16x32_bf16 v[86:89], v[152:155], v[202:205], v[86:89]
	v_mfma_f32_16x16x32_bf16 v[82:85], v[178:181], v[202:205], v[82:85]
	v_mfma_f32_16x16x32_bf16 v[70:73], v[152:155], v[214:217], v[70:73]
	v_mfma_f32_16x16x32_bf16 v[66:69], v[178:181], v[214:217], v[66:69]
	v_mfma_f32_16x16x32_bf16 v[118:121], v[174:177], v[190:193], v[118:121]
	v_mfma_f32_16x16x32_bf16 v[114:117], v[182:185], v[190:193], v[114:117]
	v_mfma_f32_16x16x32_bf16 v[102:105], v[174:177], v[198:201], v[102:105]
	v_mfma_f32_16x16x32_bf16 v[98:101], v[182:185], v[198:201], v[98:101]
	v_mfma_f32_16x16x32_bf16 v[86:89], v[174:177], v[210:213], v[86:89]
	v_mfma_f32_16x16x32_bf16 v[82:85], v[182:185], v[210:213], v[82:85]
	v_mfma_f32_16x16x32_bf16 v[70:73], v[174:177], v[218:221], v[70:73]
	v_mfma_f32_16x16x32_bf16 v[66:69], v[182:185], v[218:221], v[66:69]
	s_setprio 0
	s_barrier
; #define PG8_STAGE(bufoff, gbase, voff) do { _Pragma("unroll") for (int _i = 0; _i < 2; ++_i) \
;         __builtin_amdgcn_global_load_lds((const unsigned*)((const char*)(gbase) + (voff)[_i]), (PG8_LAS unsigned*)(lds + (bufoff) + ldsw + _i * 8192), 16, 0, 0); } while (0)
; #define PG8_LDA(dst, b, h) do { _Pragma("unroll") for (int m = 0; m < 4; ++m) _Pragma("unroll") for (int k = 0; k < 2; ++k) dst[m][k] = *(const PG8_LAS bf16x8*)(lds + PG8_SA(b, h) + aoff + m * 2048 + k * 1024); } while (0)
; #define PG8_MMA(ai, bj, At, Bt) do { __builtin_amdgcn_s_setprio(1); _Pragma("unroll") for (int m = 0; m < 4; ++m) _Pragma("unroll") for (int n = 0; n < 2; ++n) _Pragma("unroll") for (int k = 0; k < 2; ++k) \
;         acc[ai][bj][m][n] = __builtin_amdgcn_mfma_f32_16x16x32_bf16(Bt[n][k], At[m][k], acc[ai][bj][m][n], 0, 0, 0); __builtin_amdgcn_s_setprio(0); } while (0)
; #define PG8_WAIT_V(n) asm volatile("s_waitcnt vmcnt(" #n ")" ::: "memory")
; #define PG8_WAIT_L(n) asm volatile("s_waitcnt lgkmcnt(" #n ")" ::: "memory")
; #define PG8_BAR __builtin_amdgcn_s_barrier()
; #define PG8_SCHED __builtin_amdgcn_sched_barrier(0)
; template <class Epi, class Sched, bool ALIGN_EPI = false, bool SP2 = false>
; __device__ __forceinline__ void gemm_phase(PG8_LAS unsigned char* lds, const Gemm g, const Sched& S, const Epi& E) {
;     ...
;             PG8_LDA(At, 1, 1); PG8_STAGE(PG8_SB(1, 0), b3, voffB); PG8_STAGE(PG8_SB(1, 1), b3 + hstep, voffB); PG8_STAGE(PG8_SA(1, 0), a3, voffA);
;             PG8_WAIT_V(8); PG8_WAIT_L(0); PG8_BAR; PG8_MMA(1, 0, At, B0); PG8_MMA(1, 1, At, B1); PG8_BAR; PG8_SCHED;
;     __device__ __forceinline__ void operator()(const f32x4 (&acc)[2][2][4][2], const Unit& u, int wr, int wc, int fr, int fq) const {
;     ...
;             for (int gg = 0; gg < 4; ++gg) { const int g = hb * 4 + gg; const size_t offn = (size_t)(row0 + (g >> 2) * 128 + (g & 3) * 16) * D + col0;
; #pragma unroll
;                 for (int k = 0; k < 4; ++k) rin[gg][k] = *(const u32x2v*)(in + offn + (k >> 1) * 128 + (k & 1) * 16); }
	s_add_i32 s58, s58, s6
	v_lshl_add_u64 v[156:157], v[156:157], 0, s[22:23]
	s_mov_b32 m0, s58
	ds_read_b128 v[186:189], v172 offset:49152
	ds_read_b128 v[190:193], v172 offset:50176
	ds_read_b128 v[194:197], v172 offset:51200
	ds_read_b128 v[198:201], v172 offset:52224
	ds_read_b128 v[202:205], v172 offset:53248
	ds_read_b128 v[210:213], v172 offset:54272
	ds_read_b128 v[214:217], v172 offset:55296
	ds_read_b128 v[218:221], v172 offset:56320
	global_load_lds_dwordx4 v[156:157], off
	v_lshl_add_u64 v[156:157], v[166:167], 0, s[22:23]
	s_add_i32 m0, s58, 0x2000
	s_add_i32 s58, s62, s6
	global_load_lds_dwordx4 v[156:157], off
	v_lshl_add_u64 v[156:157], v[206:207], 0, s[22:23]
	s_mov_b32 m0, s58
	s_nop 0
	global_load_lds_dwordx4 v[156:157], off
	v_lshl_add_u64 v[156:157], v[222:223], 0, s[22:23]
	s_add_i32 m0, s58, 0x2000
	s_nop 0
	global_load_lds_dwordx4 v[156:157], off
	v_lshl_add_u64 v[156:157], v[224:225], 0, s[22:23]
	s_mov_b32 m0, s33
	s_nop 0
	global_load_lds_dwordx4 v[156:157], off
	v_lshl_add_u64 v[156:157], v[226:227], 0, s[22:23]
	s_mov_b32 m0, s34
	s_nop 0
	global_load_lds_dwordx4 v[156:157], off
	s_waitcnt vmcnt(8)
	s_waitcnt lgkmcnt(0)
	s_barrier
	s_setprio 1
	s_waitcnt lgkmcnt(0)
	v_mfma_f32_16x16x32_bf16 v[62:65], v[136:139], v[186:189], v[62:65]
	v_mfma_f32_16x16x32_bf16 v[58:61], v[144:147], v[186:189], v[58:61]
	v_mfma_f32_16x16x32_bf16 v[46:49], v[136:139], v[194:197], v[46:49]
	v_mfma_f32_16x16x32_bf16 v[42:45], v[144:147], v[194:197], v[42:45]
	v_mfma_f32_16x16x32_bf16 v[30:33], v[136:139], v[202:205], v[30:33]
	v_mfma_f32_16x16x32_bf16 v[26:29], v[144:147], v[202:205], v[26:29]
	v_mfma_f32_16x16x32_bf16 v[14:17], v[136:139], v[214:217], v[14:17]
	v_mfma_f32_16x16x32_bf16 v[10:13], v[144:147], v[214:217], v[10:13]
	v_mfma_f32_16x16x32_bf16 v[62:65], v[140:143], v[190:193], v[62:65]
	v_mfma_f32_16x16x32_bf16 v[58:61], v[148:151], v[190:193], v[58:61]
	v_mfma_f32_16x16x32_bf16 v[46:49], v[140:143], v[198:201], v[46:49]
	v_mfma_f32_16x16x32_bf16 v[42:45], v[148:151], v[198:201], v[42:45]
	v_mfma_f32_16x16x32_bf16 v[30:33], v[140:143], v[210:213], v[30:33]
	v_mfma_f32_16x16x32_bf16 v[26:29], v[148:151], v[210:213], v[26:29]
	v_mfma_f32_16x16x32_bf16 v[14:17], v[140:143], v[218:221], v[14:17]
	v_mfma_f32_16x16x32_bf16 v[10:13], v[148:151], v[218:221], v[10:13]
	s_setprio 0
	s_setprio 1
	v_mfma_f32_16x16x32_bf16 v[54:57], v[152:155], v[186:189], v[54:57]
	v_mfma_f32_16x16x32_bf16 v[50:53], v[178:181], v[186:189], v[50:53]
	v_mfma_f32_16x16x32_bf16 v[38:41], v[152:155], v[194:197], v[38:41]
	v_mfma_f32_16x16x32_bf16 v[34:37], v[178:181], v[194:197], v[34:37]
	v_mfma_f32_16x16x32_bf16 v[22:25], v[152:155], v[202:205], v[22:25]
	v_mfma_f32_16x16x32_bf16 v[18:21], v[178:181], v[202:205], v[18:21]
	v_mfma_f32_16x16x32_bf16 v[6:9], v[152:155], v[214:217], v[6:9]
	v_mfma_f32_16x16x32_bf16 v[2:5], v[178:181], v[214:217], v[2:5]
	v_mfma_f32_16x16x32_bf16 v[54:57], v[174:177], v[190:193], v[54:57]
	v_mfma_f32_16x16x32_bf16 v[50:53], v[182:185], v[190:193], v[50:53]
	v_mfma_f32_16x16x32_bf16 v[38:41], v[174:177], v[198:201], v[38:41]
	v_mfma_f32_16x16x32_bf16 v[34:37], v[182:185], v[198:201], v[34:37]
	v_mfma_f32_16x16x32_bf16 v[22:25], v[174:177], v[210:213], v[22:25]
	v_mfma_f32_16x16x32_bf16 v[18:21], v[182:185], v[210:213], v[18:21]
	v_mfma_f32_16x16x32_bf16 v[6:9], v[174:177], v[218:221], v[6:9]
	v_mfma_f32_16x16x32_bf16 v[2:5], v[182:185], v[218:221], v[2:5]
	s_setprio 0
	s_barrier
	s_sub_u32 s100, s31, 6
	s_cmp_eq_u32 s58, s100
	s_cbranch_scc0 .Lpf_out_a
	s_lshl_b32 s100, s13, 19
	s_lshl_b32 s101, s12, 9
	s_add_u32 s100, s100, s101
	s_add_u32 s100, s100, s46
	s_addc_u32 s101, s47, 0
	global_load_dword v240, v241, s[100:101]
.Lpf_out_a:
	s_sub_u32 s100, s31, 4
	s_cmp_eq_u32 s58, s100
	s_cbranch_scc0 .Lpf_out_b
	s_lshl_b32 s100, s13, 19
	s_lshl_b32 s101, s12, 9
	s_add_u32 s100, s100, s101
	s_add_u32 s100, s100, s46
	s_addc_u32 s101, s47, 0
	global_load_dword v240, v242, s[100:101]
.Lpf_out_b:
	s_add_u32 s80, s80, 0x100
	s_addc_u32 s81, s81, 0
	s_add_u32 s56, s56, 0x100
	s_addc_u32 s57, s57, 0
	s_cmp_ge_i32 s59, s31
	s_mov_b32 s58, s59
	s_cbranch_scc0 .LBB0_1099
	v_readlane_b32 s62, v250, 20
	s_mov_b32 s84, s62
	v_readlane_b32 s63, v250, 21

;     __host__ __device__ bool next(int i, Unit& u) const {
;         const long L = (long)i * G + c; if (L >= nwg) return false;
;         int wgid = (int)L; { const int q = nwg / NXCD, r = nwg % NXCD, xcd = wgid % NXCD, off = wgid / NXCD; wgid = (xcd < r ? xcd * (q + 1) : r * (q + 1) + (xcd - r) * q) + off; }
;         const int nig = WGM * nN, gid = wgid / nig, fm = gid * WGM, gsz = (nM - fm) < WGM ? (nM - fm) : WGM;
;         u.pm = fm + ((wgid % nig) % gsz); u.pn = (wgid % nig) / gsz; if (rev) u.pm = nM - 1 - u.pm; return true;
.LBB0_1251:
	s_or_b64 exec, exec, s[10:11]
	s_movk_i32 s38, 0xb00
	s_movk_i32 s0, 0x400
	s_waitcnt lgkmcnt(0)
	s_barrier
	s_ashr_i32 s1, s0, 31
	s_lshr_b32 s1, s1, 24
	s_add_i32 s0, s0, s1
	s_ashr_i32 s42, s0, 8
	s_lshl_b32 s10, s42, 7
	v_mov_b32_e32 v14, v158
	v_lshrrev_b32_e32 v241, 2, v158
	v_lshlrev_b32_e32 v241, 11, v241
	v_and_b32_e32 v242, 3, v158
	v_lshl_or_b32 v241, v242, 7, v241
	v_add_u32_e32 v242, 0x40000, v241
	s_cmp_lt_i32 s2, s10
	s_cselect_b64 s[14:15], -1, 0
	s_cmp_ge_i32 s2, s10
	v_readfirstlane_b32 s11, v14
	s_cbranch_scc1 .LBB0_1253
	s_lshl_b32 s0, s42, 3
	s_abs_i32 s1, s0
	v_cvt_f32_u32_e32 v0, s1
	s_lshl_b32 s6, s42, 4
	v_readlane_b32 s7, v251, 60
	s_or_b32 s6, s6, s7
	v_rcp_iflag_f32_e32 v0, v0
	v_readlane_b32 s7, v251, 15
	s_mul_i32 s6, s6, s7
	s_sub_i32 s7, 0, s1
	v_mul_f32_e32 v0, 0x4f7ffffe, v0
	v_cvt_u32_f32_e32 v0, v0
	v_readlane_b32 s8, v251, 14
	s_add_i32 s6, s6, s8
	s_abs_i32 s9, s6
	v_readfirstlane_b32 s12, v0
	s_mul_i32 s7, s7, s12
	s_mul_hi_u32 s7, s12, s7
	s_add_i32 s12, s12, s7
	s_mul_hi_u32 s7, s9, s12
	s_mul_i32 s12, s7, s1
	s_xor_b32 s8, s6, s0
	s_sub_i32 s9, s9, s12
	s_ashr_i32 s8, s8, 31
	s_add_i32 s13, s7, 1
	s_sub_i32 s12, s9, s1
	s_cmp_ge_u32 s9, s1
	s_cselect_b32 s7, s13, s7
	s_cselect_b32 s9, s12, s9
	s_add_i32 s12, s7, 1
	s_cmp_ge_u32 s9, s1
	s_cselect_b32 s1, s12, s7
	s_xor_b32 s1, s1, s8
	s_sub_i32 s1, s1, s8
	s_lshl_b32 s7, s1, 3
	s_sub_i32 s8, 0x80, s7
	s_min_i32 s8, s8, 8
	s_abs_i32 s9, s8
	v_cvt_f32_u32_e32 v0, s9
	s_sub_i32 s12, 0, s9
	s_mul_i32 s1, s1, s0
	s_sub_i32 s0, s6, s1
	v_rcp_iflag_f32_e32 v0, v0
	s_abs_i32 s1, s0
	s_xor_b32 s6, s0, s8
	s_ashr_i32 s6, s6, 31
	v_mul_f32_e32 v0, 0x4f7ffffe, v0
	v_cvt_u32_f32_e32 v0, v0
	s_nop 0
	v_readfirstlane_b32 s13, v0
	s_mul_i32 s12, s12, s13
	s_mul_hi_u32 s12, s13, s12
	s_add_i32 s13, s13, s12
	s_mul_hi_u32 s12, s1, s13
	s_mul_i32 s13, s12, s9
	s_sub_i32 s1, s1, s13
	s_add_i32 s18, s12, 1
	s_sub_i32 s13, s1, s9
	s_cmp_ge_u32 s1, s9
	s_cselect_b32 s12, s18, s12
	s_cselect_b32 s1, s13, s1
	s_add_i32 s13, s12, 1
	s_cmp_ge_u32 s1, s9
	s_cselect_b32 s1, s13, s12
	s_xor_b32 s1, s1, s6
	s_sub_i32 s12, s1, s6
	s_mul_i32 s1, s12, s8
	s_sub_i32 s0, s0, s1
	s_add_i32 s13, s0, s7
